# EpiF (GDOWN/GOUT epilogue): all-ones scale vector as 1.0 immediates (no loads, no vmcnt(0) drain of the next tile's prefetch), row sums via v_permlane16/32_swap instead of ds_bpermute; layout kept by
# baseline (speedup 1.0000x reference)
.LBB0_191:
	v_mov_b32_e32 v158, v160
	s_mov_b32 s40, s16
	v_mov_b32_e32 v159, v161
	s_mov_b32 s92, s23
	s_lshl_b32 s41, s48, 8
	s_lshl_b32 s48, s99, 8
	s_lshl_b32 s68, s92, 5
	s_add_i32 s68, s68, s48
	v_lshl_add_u32 v156, v159, 3, s68
	v_ashrrev_i32_e32 v157, 31, v156
	s_lshl_b32 s40, s40, 6
	s_add_i32 s40, s40, s41
	v_add_u32_e32 v158, s40, v158
	v_cmp_eq_u32_e32 vcc, 0, v159
	v_ashrrev_i32_e32 v159, 31, v158
	v_lshlrev_b64 v[164:165], 11, v[158:159]
	s_lshl_b32 s94, s99, 2
	s_ashr_i32 s95, s94, 31
	s_ashr_i32 s93, s92, 31
	v_mov_b32_e32 v122, 1.0
	v_mov_b32_e32 v123, 1.0
	v_mov_b32_e32 v124, 1.0
	v_mov_b32_e32 v125, 1.0
	v_mov_b32_e32 v126, 1.0
	v_mov_b32_e32 v127, 1.0
	v_mov_b32_e32 v128, 1.0
	v_mov_b32_e32 v129, 1.0
	v_mov_b32_e32 v106, 1.0
	v_mov_b32_e32 v107, 1.0
	v_mov_b32_e32 v108, 1.0
	v_mov_b32_e32 v109, 1.0
	v_mov_b32_e32 v110, 1.0
	v_mov_b32_e32 v111, 1.0
	v_mov_b32_e32 v112, 1.0
	v_mov_b32_e32 v113, 1.0
	v_pk_mul_f32 v[166:167], v[140:141], v[124:125]
	v_pk_mul_f32 v[144:145], v[144:145], v[128:129]
	v_pk_mul_f32 v[142:143], v[142:143], v[126:127]
	v_pk_mul_f32 v[140:141], v[138:139], v[122:123]
	v_mul_f32_e32 v138, v143, v143
	v_mul_f32_e32 v139, v145, v145
	v_fmac_f32_e32 v138, v142, v142
	v_fmac_f32_e32 v139, v144, v144
	v_add_f32_e32 v138, v138, v139
	v_mul_f32_e32 v139, v141, v141
	v_fmac_f32_e32 v139, v140, v140
	v_add_f32_e32 v138, v138, v139
	v_mul_f32_e32 v139, v167, v167
	v_fmac_f32_e32 v139, v166, v166
	v_add_f32_e32 v168, v139, v138
	v_cvt_pk_bf16_f32 v138, v142, v143
	v_lshl_add_u64 v[142:143], s[62:63], 0, v[164:165]
	v_cvt_pk_bf16_f32 v139, v144, v145
	v_lshl_add_u64 v[142:143], v[156:157], 1, v[142:143]
	v_pk_mul_f32 v[136:137], v[136:137], v[112:113]
	v_pk_mul_f32 v[134:135], v[134:135], v[110:111]
	v_cvt_pk_bf16_f32 v140, v140, v141
	v_cvt_pk_bf16_f32 v141, v166, v167
	global_store_dwordx4 v[142:143], v[138:141], off
	s_nop 1
	v_pk_mul_f32 v[138:139], v[132:133], v[108:109]
	v_pk_mul_f32 v[132:133], v[130:131], v[106:107]
	v_mul_f32_e32 v130, v135, v135
	v_mul_f32_e32 v131, v137, v137
	v_fmac_f32_e32 v130, v134, v134
	v_fmac_f32_e32 v131, v136, v136
	v_add_f32_e32 v130, v130, v131
	v_mul_f32_e32 v131, v133, v133
	v_fmac_f32_e32 v131, v132, v132
	v_add_f32_e32 v130, v130, v131
	v_mul_f32_e32 v131, v139, v139
	v_fmac_f32_e32 v131, v138, v138
	v_add_f32_e32 v130, v131, v130
	v_cvt_pk_bf16_f32 v131, v136, v137
	v_add_f32_e32 v140, v168, v130
	v_cvt_pk_bf16_f32 v130, v134, v135
	v_cvt_pk_bf16_f32 v132, v132, v133
	v_cvt_pk_bf16_f32 v133, v138, v139
	global_store_dwordx4 v[142:143], v[130:133], off offset:256
	s_nop 1
	v_and_b32_e32 v131, 64, v231
	v_xor_b32_e32 v130, 16, v231
	v_add_u32_e32 v131, 64, v131
	v_cmp_lt_i32_e64 s[40:41], v130, v131
	v_xor_b32_e32 v133, 32, v231
	s_nop 0
	v_cndmask_b32_e64 v130, v231, v130, s[40:41]
	v_lshlrev_b32_e32 v132, 2, v130
	v_mov_b32_e32 v132, v140
	v_mov_b32_e32 v130, v140
	s_nop 1
	v_permlane16_swap_b32_e32 v132, v130
	v_cmp_lt_i32_e64 s[40:41], v133, v131
	s_waitcnt lgkmcnt(0)
	v_add_f32_e32 v130, v132, v130
	v_cndmask_b32_e64 v131, v231, v133, s[40:41]
	v_lshlrev_b32_e32 v133, 2, v131
	v_mov_b32_e32 v131, v130
	s_nop 1
	v_permlane32_swap_b32_e32 v130, v131
	s_and_saveexec_b64 s[40:41], vcc
	s_cbranch_execz .LBB0_193
	v_lshlrev_b64 v[134:135], 6, v[158:159]
	v_lshl_add_u64 v[134:135], s[76:77], 0, v[134:135]
	v_lshl_add_u64 v[134:135], s[94:95], 2, v[134:135]
	v_lshl_add_u64 v[134:135], s[92:93], 2, v[134:135]
	s_waitcnt lgkmcnt(0)
	v_add_f32_e32 v130, v130, v131
	global_store_dword v[134:135], v130, off
.LBB0_193:
	s_or_b64 exec, exec, s[40:41]
	v_pk_mul_f32 v[120:121], v[120:121], v[128:129]
	v_pk_mul_f32 v[118:119], v[118:119], v[126:127]
	v_pk_mul_f32 v[136:137], v[116:117], v[124:125]
	v_pk_mul_f32 v[116:117], v[114:115], v[122:123]
	v_mul_f32_e32 v114, v119, v119
	v_mul_f32_e32 v115, v121, v121
	v_fmac_f32_e32 v114, v118, v118
	v_fmac_f32_e32 v115, v120, v120
	v_add_f32_e32 v114, v114, v115
	v_mul_f32_e32 v115, v117, v117
	v_fmac_f32_e32 v115, v116, v116
	v_add_f32_e32 v114, v114, v115
	v_mul_f32_e32 v115, v137, v137
	v_fmac_f32_e32 v115, v136, v136
	v_pk_mul_f32 v[104:105], v[104:105], v[112:113]
	v_pk_mul_f32 v[102:103], v[102:103], v[110:111]
	v_add_f32_e32 v138, v115, v114
	v_cvt_pk_bf16_f32 v115, v120, v121
	v_pk_mul_f32 v[120:121], v[98:99], v[106:107]
	v_mul_f32_e32 v98, v103, v103
	v_mul_f32_e32 v99, v105, v105
	v_fmac_f32_e32 v98, v102, v102
	v_fmac_f32_e32 v99, v104, v104
	v_add_f32_e32 v98, v98, v99
	v_mul_f32_e32 v99, v121, v121
	v_cvt_pk_bf16_f32 v114, v118, v119
	v_pk_mul_f32 v[118:119], v[100:101], v[108:109]
	v_fmac_f32_e32 v99, v120, v120
	v_add_f32_e32 v98, v98, v99
	v_mul_f32_e32 v99, v119, v119
	v_fmac_f32_e32 v99, v118, v118
	v_add_f32_e32 v98, v99, v98
	v_add_f32_e32 v101, v138, v98
	v_cvt_pk_bf16_f32 v116, v116, v117
	v_cvt_pk_bf16_f32 v117, v136, v137
	v_mov_b32_e32 v132, v101
	v_mov_b32_e32 v136, v101
	s_nop 1
	v_permlane16_swap_b32_e32 v132, v136
	v_add_u32_e32 v130, 16, v158
	s_waitcnt lgkmcnt(1)
	v_ashrrev_i32_e32 v131, 31, v130
	v_lshlrev_b64 v[134:135], 11, v[130:131]
	v_lshl_add_u64 v[98:99], s[62:63], 0, v[134:135]
	v_lshl_add_u64 v[134:135], v[156:157], 1, v[98:99]
	s_waitcnt lgkmcnt(0)
	v_add_f32_e32 v98, v132, v136
	v_mov_b32_e32 v99, v98
	s_nop 1
	v_permlane32_swap_b32_e32 v98, v99
	global_store_dwordx4 v[134:135], v[114:117], off
	v_cvt_pk_bf16_f32 v100, v102, v103
	v_cvt_pk_bf16_f32 v101, v104, v105
	v_cvt_pk_bf16_f32 v102, v120, v121
	v_cvt_pk_bf16_f32 v103, v118, v119
	global_store_dwordx4 v[134:135], v[100:103], off offset:256
	s_and_saveexec_b64 s[40:41], vcc
	s_cbranch_execz .LBB0_195
	v_lshlrev_b64 v[100:101], 6, v[130:131]
	v_lshl_add_u64 v[100:101], s[76:77], 0, v[100:101]
	v_lshl_add_u64 v[100:101], s[94:95], 2, v[100:101]
	v_lshl_add_u64 v[100:101], s[92:93], 2, v[100:101]
	s_waitcnt lgkmcnt(0)
	v_add_f32_e32 v98, v98, v99
	global_store_dword v[100:101], v98, off
.LBB0_195:
	s_or_b64 exec, exec, s[40:41]
	v_pk_mul_f32 v[96:97], v[96:97], v[128:129]
	v_pk_mul_f32 v[94:95], v[94:95], v[126:127]
	v_pk_mul_f32 v[102:103], v[92:93], v[124:125]
	v_pk_mul_f32 v[92:93], v[90:91], v[122:123]
	v_mul_f32_e32 v90, v95, v95
	v_mul_f32_e32 v91, v97, v97
	v_fmac_f32_e32 v90, v94, v94
	v_fmac_f32_e32 v91, v96, v96
	v_add_f32_e32 v90, v90, v91
	v_mul_f32_e32 v91, v93, v93
	v_fmac_f32_e32 v91, v92, v92
	v_add_f32_e32 v90, v90, v91
	v_mul_f32_e32 v91, v103, v103
	v_fmac_f32_e32 v91, v102, v102
	v_pk_mul_f32 v[88:89], v[88:89], v[112:113]
	v_pk_mul_f32 v[86:87], v[86:87], v[110:111]
	v_add_f32_e32 v104, v91, v90
	v_cvt_pk_bf16_f32 v91, v96, v97
	v_pk_mul_f32 v[96:97], v[82:83], v[106:107]
	v_mul_f32_e32 v82, v87, v87
	v_mul_f32_e32 v83, v89, v89
	v_fmac_f32_e32 v82, v86, v86
	v_fmac_f32_e32 v83, v88, v88
	v_add_f32_e32 v82, v82, v83
	v_mul_f32_e32 v83, v97, v97
	v_cvt_pk_bf16_f32 v90, v94, v95
	v_pk_mul_f32 v[94:95], v[84:85], v[108:109]
	v_fmac_f32_e32 v83, v96, v96
	v_add_f32_e32 v82, v82, v83
	v_mul_f32_e32 v83, v95, v95
	v_fmac_f32_e32 v83, v94, v94
	v_add_f32_e32 v82, v83, v82
	v_add_f32_e32 v85, v104, v82
	v_cvt_pk_bf16_f32 v92, v92, v93
	v_cvt_pk_bf16_f32 v93, v102, v103
	v_mov_b32_e32 v132, v85
	v_mov_b32_e32 v102, v85
	s_nop 1
	v_permlane16_swap_b32_e32 v132, v102
	v_add_u32_e32 v98, 32, v158
	s_waitcnt lgkmcnt(1)
	v_ashrrev_i32_e32 v99, 31, v98
	v_lshlrev_b64 v[100:101], 11, v[98:99]
	v_lshl_add_u64 v[82:83], s[62:63], 0, v[100:101]
	v_lshl_add_u64 v[100:101], v[156:157], 1, v[82:83]
	s_waitcnt lgkmcnt(0)
	v_add_f32_e32 v82, v132, v102
	v_mov_b32_e32 v83, v82
	s_nop 1
	v_permlane32_swap_b32_e32 v82, v83
	global_store_dwordx4 v[100:101], v[90:93], off
	v_cvt_pk_bf16_f32 v84, v86, v87
	v_cvt_pk_bf16_f32 v85, v88, v89
	v_cvt_pk_bf16_f32 v86, v96, v97
	v_cvt_pk_bf16_f32 v87, v94, v95
	global_store_dwordx4 v[100:101], v[84:87], off offset:256
	s_and_saveexec_b64 s[40:41], vcc
	s_cbranch_execz .LBB0_197
	v_lshlrev_b64 v[84:85], 6, v[98:99]
	v_lshl_add_u64 v[84:85], s[76:77], 0, v[84:85]
	v_lshl_add_u64 v[84:85], s[94:95], 2, v[84:85]
	v_lshl_add_u64 v[84:85], s[92:93], 2, v[84:85]
	s_waitcnt lgkmcnt(0)
	v_add_f32_e32 v82, v82, v83
	global_store_dword v[84:85], v82, off
.LBB0_197:
	s_or_b64 exec, exec, s[40:41]
	v_pk_mul_f32 v[80:81], v[80:81], v[128:129]
	v_pk_mul_f32 v[78:79], v[78:79], v[126:127]
	v_pk_mul_f32 v[86:87], v[76:77], v[124:125]
	v_pk_mul_f32 v[76:77], v[74:75], v[122:123]
	v_mul_f32_e32 v74, v79, v79
	v_mul_f32_e32 v75, v81, v81
	v_fmac_f32_e32 v74, v78, v78
	v_fmac_f32_e32 v75, v80, v80
	v_add_f32_e32 v74, v74, v75
	v_mul_f32_e32 v75, v77, v77
	v_fmac_f32_e32 v75, v76, v76
	v_add_f32_e32 v74, v74, v75
	v_mul_f32_e32 v75, v87, v87
	v_fmac_f32_e32 v75, v86, v86
	v_pk_mul_f32 v[72:73], v[72:73], v[112:113]
	v_pk_mul_f32 v[70:71], v[70:71], v[110:111]
	v_add_f32_e32 v88, v75, v74
	v_cvt_pk_bf16_f32 v75, v80, v81
	v_pk_mul_f32 v[80:81], v[66:67], v[106:107]
	v_mul_f32_e32 v66, v71, v71
	v_mul_f32_e32 v67, v73, v73
	v_fmac_f32_e32 v66, v70, v70
	v_fmac_f32_e32 v67, v72, v72
	v_add_f32_e32 v66, v66, v67
	v_mul_f32_e32 v67, v81, v81
	v_cvt_pk_bf16_f32 v74, v78, v79
	v_pk_mul_f32 v[78:79], v[68:69], v[108:109]
	v_fmac_f32_e32 v67, v80, v80
	v_add_f32_e32 v66, v66, v67
	v_mul_f32_e32 v67, v79, v79
	v_fmac_f32_e32 v67, v78, v78
	v_add_f32_e32 v66, v67, v66
	v_add_f32_e32 v69, v88, v66
	v_cvt_pk_bf16_f32 v76, v76, v77
	v_cvt_pk_bf16_f32 v77, v86, v87
	v_mov_b32_e32 v132, v69
	v_mov_b32_e32 v86, v69
	s_nop 1
	v_permlane16_swap_b32_e32 v132, v86
	v_add_u32_e32 v82, 48, v158
	s_waitcnt lgkmcnt(1)
	v_ashrrev_i32_e32 v83, 31, v82
	v_lshlrev_b64 v[84:85], 11, v[82:83]
	v_lshl_add_u64 v[66:67], s[62:63], 0, v[84:85]
	v_lshl_add_u64 v[84:85], v[156:157], 1, v[66:67]
	s_waitcnt lgkmcnt(0)
	v_add_f32_e32 v66, v132, v86
	v_mov_b32_e32 v67, v66
	s_nop 1
	v_permlane32_swap_b32_e32 v66, v67
	global_store_dwordx4 v[84:85], v[74:77], off
	v_cvt_pk_bf16_f32 v68, v70, v71
	v_cvt_pk_bf16_f32 v69, v72, v73
	v_cvt_pk_bf16_f32 v70, v80, v81
	v_cvt_pk_bf16_f32 v71, v78, v79
	global_store_dwordx4 v[84:85], v[68:71], off offset:256
	s_and_saveexec_b64 s[40:41], vcc
	s_cbranch_execz .LBB0_199
	v_lshlrev_b64 v[68:69], 6, v[82:83]
	v_lshl_add_u64 v[68:69], s[76:77], 0, v[68:69]
	v_lshl_add_u64 v[68:69], s[94:95], 2, v[68:69]
	v_lshl_add_u64 v[68:69], s[92:93], 2, v[68:69]
	s_waitcnt lgkmcnt(0)
	v_add_f32_e32 v66, v66, v67
	global_store_dword v[68:69], v66, off
.LBB0_199:
	s_or_b64 exec, exec, s[40:41]
	v_pk_mul_f32 v[64:65], v[64:65], v[128:129]
	v_pk_mul_f32 v[62:63], v[62:63], v[126:127]
	v_pk_mul_f32 v[70:71], v[60:61], v[124:125]
	v_pk_mul_f32 v[60:61], v[58:59], v[122:123]
	v_mul_f32_e32 v58, v63, v63
	v_mul_f32_e32 v59, v65, v65
	v_fmac_f32_e32 v58, v62, v62
	v_fmac_f32_e32 v59, v64, v64
	v_add_f32_e32 v58, v58, v59
	v_mul_f32_e32 v59, v61, v61
	v_fmac_f32_e32 v59, v60, v60
	v_add_f32_e32 v58, v58, v59
	v_mul_f32_e32 v59, v71, v71
	v_fmac_f32_e32 v59, v70, v70
	v_pk_mul_f32 v[56:57], v[56:57], v[112:113]
	v_pk_mul_f32 v[54:55], v[54:55], v[110:111]
	v_add_f32_e32 v72, v59, v58
	v_cvt_pk_bf16_f32 v59, v64, v65
	v_pk_mul_f32 v[64:65], v[50:51], v[106:107]
	v_mul_f32_e32 v50, v55, v55
	v_mul_f32_e32 v51, v57, v57
	v_fmac_f32_e32 v50, v54, v54
	v_fmac_f32_e32 v51, v56, v56
	v_add_f32_e32 v50, v50, v51
	v_mul_f32_e32 v51, v65, v65
	v_cvt_pk_bf16_f32 v58, v62, v63
	v_pk_mul_f32 v[62:63], v[52:53], v[108:109]
	v_fmac_f32_e32 v51, v64, v64
	v_add_f32_e32 v50, v50, v51
	v_mul_f32_e32 v51, v63, v63
	v_fmac_f32_e32 v51, v62, v62
	v_add_f32_e32 v50, v51, v50
	v_add_f32_e32 v53, v72, v50
	v_cvt_pk_bf16_f32 v60, v60, v61
	v_cvt_pk_bf16_f32 v61, v70, v71
	v_mov_b32_e32 v132, v53
	v_mov_b32_e32 v70, v53
	s_nop 1
	v_permlane16_swap_b32_e32 v132, v70
	v_add_u32_e32 v66, 0x80, v158
	s_waitcnt lgkmcnt(1)
	v_ashrrev_i32_e32 v67, 31, v66
	v_lshlrev_b64 v[68:69], 11, v[66:67]
	v_lshl_add_u64 v[50:51], s[62:63], 0, v[68:69]
	v_lshl_add_u64 v[68:69], v[156:157], 1, v[50:51]
	s_waitcnt lgkmcnt(0)
	v_add_f32_e32 v50, v132, v70
	v_mov_b32_e32 v51, v50
	s_nop 1
	v_permlane32_swap_b32_e32 v50, v51
	global_store_dwordx4 v[68:69], v[58:61], off
	v_cvt_pk_bf16_f32 v52, v54, v55
	v_cvt_pk_bf16_f32 v53, v56, v57
	v_cvt_pk_bf16_f32 v54, v64, v65
	v_cvt_pk_bf16_f32 v55, v62, v63
	global_store_dwordx4 v[68:69], v[52:55], off offset:256
	s_and_saveexec_b64 s[40:41], vcc
	s_cbranch_execz .LBB0_201
	v_lshlrev_b64 v[52:53], 6, v[66:67]
	v_lshl_add_u64 v[52:53], s[76:77], 0, v[52:53]
	v_lshl_add_u64 v[52:53], s[94:95], 2, v[52:53]
	v_lshl_add_u64 v[52:53], s[92:93], 2, v[52:53]
	s_waitcnt lgkmcnt(0)
	v_add_f32_e32 v50, v50, v51
	global_store_dword v[52:53], v50, off
.LBB0_201:
	s_or_b64 exec, exec, s[40:41]
	v_pk_mul_f32 v[48:49], v[48:49], v[128:129]
	v_pk_mul_f32 v[46:47], v[46:47], v[126:127]
	v_pk_mul_f32 v[54:55], v[44:45], v[124:125]
	v_pk_mul_f32 v[44:45], v[42:43], v[122:123]
	v_mul_f32_e32 v42, v47, v47
	v_mul_f32_e32 v43, v49, v49
	v_fmac_f32_e32 v42, v46, v46
	v_fmac_f32_e32 v43, v48, v48
	v_add_f32_e32 v42, v42, v43
	v_mul_f32_e32 v43, v45, v45
	v_fmac_f32_e32 v43, v44, v44
	v_add_f32_e32 v42, v42, v43
	v_mul_f32_e32 v43, v55, v55
	v_fmac_f32_e32 v43, v54, v54
	v_pk_mul_f32 v[40:41], v[40:41], v[112:113]
	v_pk_mul_f32 v[38:39], v[38:39], v[110:111]
	v_add_f32_e32 v56, v43, v42
	v_cvt_pk_bf16_f32 v43, v48, v49
	v_pk_mul_f32 v[48:49], v[34:35], v[106:107]
	v_mul_f32_e32 v34, v39, v39
	v_mul_f32_e32 v35, v41, v41
	v_fmac_f32_e32 v34, v38, v38
	v_fmac_f32_e32 v35, v40, v40
	v_add_f32_e32 v34, v34, v35
	v_mul_f32_e32 v35, v49, v49
	v_cvt_pk_bf16_f32 v42, v46, v47
	v_pk_mul_f32 v[46:47], v[36:37], v[108:109]
	v_fmac_f32_e32 v35, v48, v48
	v_add_f32_e32 v34, v34, v35
	v_mul_f32_e32 v35, v47, v47
	v_fmac_f32_e32 v35, v46, v46
	v_add_f32_e32 v34, v35, v34
	v_add_f32_e32 v37, v56, v34
	v_cvt_pk_bf16_f32 v44, v44, v45
	v_cvt_pk_bf16_f32 v45, v54, v55
	v_mov_b32_e32 v132, v37
	v_mov_b32_e32 v54, v37
	s_nop 1
	v_permlane16_swap_b32_e32 v132, v54
	v_add_u32_e32 v50, 0x90, v158
	s_waitcnt lgkmcnt(1)
	v_ashrrev_i32_e32 v51, 31, v50
	v_lshlrev_b64 v[52:53], 11, v[50:51]
	v_lshl_add_u64 v[34:35], s[62:63], 0, v[52:53]
	v_lshl_add_u64 v[52:53], v[156:157], 1, v[34:35]
	s_waitcnt lgkmcnt(0)
	v_add_f32_e32 v34, v132, v54
	v_mov_b32_e32 v35, v34
	s_nop 1
	v_permlane32_swap_b32_e32 v34, v35
	global_store_dwordx4 v[52:53], v[42:45], off
	v_cvt_pk_bf16_f32 v36, v38, v39
	v_cvt_pk_bf16_f32 v37, v40, v41
	v_cvt_pk_bf16_f32 v38, v48, v49
	v_cvt_pk_bf16_f32 v39, v46, v47
	global_store_dwordx4 v[52:53], v[36:39], off offset:256
	s_and_saveexec_b64 s[40:41], vcc
	s_cbranch_execz .LBB0_203
	v_lshlrev_b64 v[36:37], 6, v[50:51]
	v_lshl_add_u64 v[36:37], s[76:77], 0, v[36:37]
	v_lshl_add_u64 v[36:37], s[94:95], 2, v[36:37]
	v_lshl_add_u64 v[36:37], s[92:93], 2, v[36:37]
	s_waitcnt lgkmcnt(0)
	v_add_f32_e32 v34, v34, v35
	global_store_dword v[36:37], v34, off
.LBB0_203:
	s_or_b64 exec, exec, s[40:41]
	v_pk_mul_f32 v[32:33], v[32:33], v[128:129]
	v_pk_mul_f32 v[30:31], v[30:31], v[126:127]
	v_pk_mul_f32 v[38:39], v[28:29], v[124:125]
	v_pk_mul_f32 v[28:29], v[26:27], v[122:123]
	v_mul_f32_e32 v26, v31, v31
	v_mul_f32_e32 v27, v33, v33
	v_fmac_f32_e32 v26, v30, v30
	v_fmac_f32_e32 v27, v32, v32
	v_add_f32_e32 v26, v26, v27
	v_mul_f32_e32 v27, v29, v29
	v_fmac_f32_e32 v27, v28, v28
	v_add_f32_e32 v26, v26, v27
	v_mul_f32_e32 v27, v39, v39
	v_fmac_f32_e32 v27, v38, v38
	v_pk_mul_f32 v[24:25], v[24:25], v[112:113]
	v_pk_mul_f32 v[22:23], v[22:23], v[110:111]
	v_add_f32_e32 v40, v27, v26
	v_cvt_pk_bf16_f32 v27, v32, v33
	v_pk_mul_f32 v[32:33], v[18:19], v[106:107]
	v_mul_f32_e32 v18, v23, v23
	v_mul_f32_e32 v19, v25, v25
	v_fmac_f32_e32 v18, v22, v22
	v_fmac_f32_e32 v19, v24, v24
	v_add_f32_e32 v18, v18, v19
	v_mul_f32_e32 v19, v33, v33
	v_cvt_pk_bf16_f32 v26, v30, v31
	v_pk_mul_f32 v[30:31], v[20:21], v[108:109]
	v_fmac_f32_e32 v19, v32, v32
	v_add_f32_e32 v18, v18, v19
	v_mul_f32_e32 v19, v31, v31
	v_fmac_f32_e32 v19, v30, v30
	v_add_f32_e32 v18, v19, v18
	v_add_f32_e32 v21, v40, v18
	v_cvt_pk_bf16_f32 v28, v28, v29
	v_cvt_pk_bf16_f32 v29, v38, v39
	v_mov_b32_e32 v132, v21
	v_mov_b32_e32 v38, v21
	s_nop 1
	v_permlane16_swap_b32_e32 v132, v38
	v_add_u32_e32 v34, 0xa0, v158
	s_waitcnt lgkmcnt(1)
	v_ashrrev_i32_e32 v35, 31, v34
	v_lshlrev_b64 v[36:37], 11, v[34:35]
	v_lshl_add_u64 v[18:19], s[62:63], 0, v[36:37]
	v_lshl_add_u64 v[36:37], v[156:157], 1, v[18:19]
	s_waitcnt lgkmcnt(0)
	v_add_f32_e32 v18, v132, v38
	v_mov_b32_e32 v19, v18
	s_nop 1
	v_permlane32_swap_b32_e32 v18, v19
	global_store_dwordx4 v[36:37], v[26:29], off
	v_cvt_pk_bf16_f32 v20, v22, v23
	v_cvt_pk_bf16_f32 v21, v24, v25
	v_cvt_pk_bf16_f32 v22, v32, v33
	v_cvt_pk_bf16_f32 v23, v30, v31
	global_store_dwordx4 v[36:37], v[20:23], off offset:256
	s_and_saveexec_b64 s[40:41], vcc
	s_cbranch_execz .LBB0_205
	v_lshlrev_b64 v[20:21], 6, v[34:35]
	v_lshl_add_u64 v[20:21], s[76:77], 0, v[20:21]
	v_lshl_add_u64 v[20:21], s[94:95], 2, v[20:21]
	v_lshl_add_u64 v[20:21], s[92:93], 2, v[20:21]
	s_waitcnt lgkmcnt(0)
	v_add_f32_e32 v18, v18, v19
	global_store_dword v[20:21], v18, off
.LBB0_205:
	s_or_b64 exec, exec, s[40:41]
	v_pk_mul_f32 v[16:17], v[16:17], v[128:129]
	v_pk_mul_f32 v[14:15], v[14:15], v[126:127]
	v_pk_mul_f32 v[22:23], v[12:13], v[124:125]
	v_pk_mul_f32 v[12:13], v[10:11], v[122:123]
	v_mul_f32_e32 v10, v15, v15
	v_mul_f32_e32 v11, v17, v17
	v_fmac_f32_e32 v10, v14, v14
	v_fmac_f32_e32 v11, v16, v16
	v_add_f32_e32 v10, v10, v11
	v_mul_f32_e32 v11, v13, v13
	v_fmac_f32_e32 v11, v12, v12
	v_add_f32_e32 v10, v10, v11
	v_mul_f32_e32 v11, v23, v23
	v_fmac_f32_e32 v11, v22, v22
	v_pk_mul_f32 v[8:9], v[8:9], v[112:113]
	v_pk_mul_f32 v[6:7], v[6:7], v[110:111]
	v_add_f32_e32 v24, v11, v10
	v_cvt_pk_bf16_f32 v11, v16, v17
	v_pk_mul_f32 v[16:17], v[2:3], v[106:107]
	v_mul_f32_e32 v2, v7, v7
	v_mul_f32_e32 v3, v9, v9
	v_fmac_f32_e32 v2, v6, v6
	v_fmac_f32_e32 v3, v8, v8
	v_add_f32_e32 v2, v2, v3
	v_mul_f32_e32 v3, v17, v17
	v_cvt_pk_bf16_f32 v10, v14, v15
	v_pk_mul_f32 v[14:15], v[4:5], v[108:109]
	v_fmac_f32_e32 v3, v16, v16
	v_add_f32_e32 v2, v2, v3
	v_mul_f32_e32 v3, v15, v15
	v_fmac_f32_e32 v3, v14, v14
	v_add_f32_e32 v2, v3, v2
	v_add_f32_e32 v5, v24, v2
	v_cvt_pk_bf16_f32 v12, v12, v13
	v_cvt_pk_bf16_f32 v13, v22, v23
	v_mov_b32_e32 v132, v5
	v_mov_b32_e32 v22, v5
	s_nop 1
	v_permlane16_swap_b32_e32 v132, v22
	v_add_u32_e32 v18, 0xb0, v158
	s_waitcnt lgkmcnt(1)
	v_ashrrev_i32_e32 v19, 31, v18
	v_lshlrev_b64 v[20:21], 11, v[18:19]
	v_lshl_add_u64 v[2:3], s[62:63], 0, v[20:21]
	v_lshl_add_u64 v[20:21], v[156:157], 1, v[2:3]
	s_waitcnt lgkmcnt(0)
	v_add_f32_e32 v2, v132, v22
	v_mov_b32_e32 v3, v2
	s_nop 1
	v_permlane32_swap_b32_e32 v2, v3
	global_store_dwordx4 v[20:21], v[10:13], off
	v_cvt_pk_bf16_f32 v4, v6, v7
	v_cvt_pk_bf16_f32 v5, v8, v9
	v_cvt_pk_bf16_f32 v6, v16, v17
	v_cvt_pk_bf16_f32 v7, v14, v15
	global_store_dwordx4 v[20:21], v[4:7], off offset:256
	s_and_saveexec_b64 s[40:41], vcc
	s_cbranch_execz .LBB0_207
	v_lshlrev_b64 v[4:5], 6, v[18:19]
	v_lshl_add_u64 v[4:5], s[76:77], 0, v[4:5]
	v_lshl_add_u64 v[4:5], s[94:95], 2, v[4:5]
	v_lshl_add_u64 v[4:5], s[92:93], 2, v[4:5]
	s_waitcnt lgkmcnt(0)
	v_add_f32_e32 v2, v2, v3
	global_store_dword v[4:5], v2, off

.LBB0_228:
	s_nop 0
	s_nop 0
	s_nop 0
	s_nop 0
	s_mov_b64 s[26:27], 0
